# all edits + attention boundary mask software-pipelined over two scalar mask registers (no s_nop fillers)
# speedup vs baseline: 1.0020x; 1.0020x over previous
; __device__ __forceinline__ void attn_chain(LAS unsigned char* lds, const bf16* Qb, const bf16* Kb, const bf16* Vb, bf16* Ob, float* lseb, int g0, int wave, int lane) {
;     ...
;                 if (t == 0 || t == 4) { const int dbase = 32 * t + 4 * hi - r32;
; #pragma unroll
;                   for (int i = 0; i < 16; ++i) if ((unsigned)(dbase + (i & 3) + 8 * (i >> 2)) > 128u) sa[i] = -1e30f; }
.LBB0_710:
	s_andn2_b64 vcc, exec, s[6:7]
	s_cbranch_vccnz .LBB0_641
	s_mul_i32 s3, s14, 0xffffff60
	s_add_i32 s3, s3, s81
	v_add_u32_e32 v170, s3, v167
	s_movk_i32 s3, 0x81
	v_add_u32_e32 v253, 0xffffff80, v170
	v_cmp_gt_u32_e64 s[90:91], s3, v170
	v_cmp_lt_u32_e64 s[98:99], s95, v253
	v_add_u32_e32 v254, 0xffffff81, v170
	v_cndmask_b32_e64 v64, v232, v64, s[90:91]
	v_cmp_lt_u32_e64 s[90:91], s95, v254
	v_add_u32_e32 v253, 0xffffff82, v170
	v_cndmask_b32_e64 v65, v232, v65, s[98:99]
	v_cmp_lt_u32_e64 s[98:99], s95, v253
	v_add_u32_e32 v254, 0xffffff87, v170
	v_cndmask_b32_e64 v66, v232, v66, s[90:91]
	v_cmp_lt_u32_e64 s[90:91], s95, v254
	v_add_u32_e32 v253, 0xffffff88, v170
	v_cndmask_b32_e64 v67, v232, v67, s[98:99]
	v_cmp_lt_u32_e64 s[98:99], s95, v253
	v_add_u32_e32 v254, 0xffffff89, v170
	v_cndmask_b32_e64 v68, v232, v68, s[90:91]
	v_cmp_lt_u32_e64 s[90:91], s95, v254
	v_add_u32_e32 v253, 0xffffff8a, v170
	v_cndmask_b32_e64 v69, v232, v69, s[98:99]
	v_cmp_lt_u32_e64 s[98:99], s95, v253
	v_add_u32_e32 v254, 0xffffff8f, v170
	v_cndmask_b32_e64 v70, v232, v70, s[90:91]
	v_cmp_lt_u32_e64 s[90:91], s95, v254
	v_add_u32_e32 v253, 0xffffff90, v170
	v_cndmask_b32_e64 v71, v232, v71, s[98:99]
	v_cmp_lt_u32_e64 s[98:99], s95, v253
	v_add_u32_e32 v254, 0xffffff91, v170
	v_cndmask_b32_e64 v72, v232, v72, s[90:91]
	v_cmp_lt_u32_e64 s[90:91], s95, v254
	v_add_u32_e32 v253, 0xffffff92, v170
	v_cndmask_b32_e64 v73, v232, v73, s[98:99]
	v_cmp_lt_u32_e64 s[98:99], s95, v253
	v_add_u32_e32 v254, 0xffffff97, v170
	v_cndmask_b32_e64 v74, v232, v74, s[90:91]
	v_cmp_lt_u32_e64 s[90:91], s95, v254
	v_add_u32_e32 v253, 0xffffff98, v170
	v_cndmask_b32_e64 v75, v232, v75, s[98:99]
	v_cmp_lt_u32_e64 s[98:99], s95, v253
	v_add_u32_e32 v254, 0xffffff99, v170
	v_cndmask_b32_e64 v76, v232, v76, s[90:91]
	v_cmp_lt_u32_e64 s[90:91], s95, v254
	v_add_u32_e32 v253, 0xffffff9a, v170
	v_cndmask_b32_e64 v77, v232, v77, s[98:99]
	v_cmp_lt_u32_e64 s[98:99], s95, v253
	v_cndmask_b32_e64 v78, v232, v78, s[90:91]
	v_cndmask_b32_e64 v79, v232, v79, s[98:99]
	s_branch .LBB0_641
